# natten dense (prefix) tiles: lazy online-softmax rescale (threshold 8), as already in the masked tiles and the MLA loop
# baseline (speedup 1.0000x reference)
.LBB0_435:
	s_andn2_b64 vcc, exec, s[86:87]
	s_cbranch_vccnz .LBB0_442
	v_lshl_add_u32 v162, s3, 1, v215
	s_nop 6
	ds_read_b128 v[2:5], v162
	ds_read_b128 v[6:9], v162 offset:32
	ds_read_b128 v[10:13], v192 offset:47104
	ds_read_b128 v[164:167], v192 offset:47136
	s_waitcnt lgkmcnt(3)
	v_mfma_f32_32x32x16_bf16 v[34:49], v[2:5], v[130:133], 0
	s_waitcnt lgkmcnt(1)
	v_mfma_f32_32x32x16_bf16 v[18:33], v[2:5], v[10:13], 0
	ds_read_b128 v[2:5], v162 offset:64
	ds_read_b128 v[168:171], v192 offset:47168
	v_mfma_f32_32x32x16_bf16 v[34:49], v[6:9], v[134:137], v[34:49]
	s_waitcnt lgkmcnt(2)
	v_mfma_f32_32x32x16_bf16 v[18:33], v[6:9], v[164:167], v[18:33]
	s_waitcnt lgkmcnt(1)
	v_mfma_f32_32x32x16_bf16 v[34:49], v[2:5], v[138:141], v[34:49]
	s_waitcnt lgkmcnt(0)
	v_mfma_f32_32x32x16_bf16 v[18:33], v[2:5], v[168:171], v[18:33]
	ds_read_b128 v[2:5], v162 offset:96
	ds_read_b128 v[172:175], v192 offset:47200
	ds_read_b128 v[176:179], v162 offset:4640
	s_waitcnt lgkmcnt(2)
	v_mfma_f32_32x32x16_bf16 v[34:49], v[2:5], v[142:145], v[34:49]
	s_waitcnt lgkmcnt(1)
	v_mfma_f32_32x32x16_bf16 v[18:33], v[2:5], v[172:175], v[18:33]
	ds_read_b128 v[2:5], v162 offset:4608
	s_waitcnt lgkmcnt(0)
	v_mfma_f32_32x32x16_bf16 v[50:65], v[2:5], v[130:133], 0
	v_mfma_f32_32x32x16_bf16 v[2:17], v[2:5], v[10:13], 0
	v_mfma_f32_32x32x16_bf16 v[2:17], v[176:179], v[164:167], v[2:17]
	ds_read_b128 v[164:167], v162 offset:4672
	v_mfma_f32_32x32x16_bf16 v[50:65], v[176:179], v[134:137], v[50:65]
	s_waitcnt lgkmcnt(0)
	v_mfma_f32_32x32x16_bf16 v[50:65], v[164:167], v[138:141], v[50:65]
	v_mfma_f32_32x32x16_bf16 v[2:17], v[164:167], v[168:171], v[2:17]
	ds_read_b128 v[164:167], v162 offset:4704
	v_xor_b32_e32 v162, 32, v200
	s_waitcnt lgkmcnt(0)
	v_mfma_f32_32x32x16_bf16 v[50:65], v[164:167], v[142:145], v[50:65]
	v_mfma_f32_32x32x16_bf16 v[2:17], v[164:167], v[172:175], v[2:17]
	v_and_b32_e32 v164, 64, v200
	v_add_u32_e32 v164, 64, v164
	v_cmp_lt_i32_e32 vcc, v162, v164
	v_max_f32_e32 v164, v34, v34
	s_nop 0
	v_cndmask_b32_e32 v162, v200, v162, vcc
	v_lshlrev_b32_e32 v222, 2, v162
	v_max_f32_e32 v162, v35, v35
	v_max_f32_e32 v162, v164, v162
	v_max3_f32 v162, v162, v36, v37
	v_max3_f32 v162, v162, v38, v39
	v_max3_f32 v162, v162, v40, v41
	v_max3_f32 v162, v162, v42, v43
	v_max3_f32 v162, v162, v44, v45
	v_max3_f32 v162, v162, v46, v47
	v_max3_f32 v162, v162, v48, v49
	v_max3_f32 v162, v162, v50, v51
	v_max3_f32 v162, v162, v52, v53
	v_max3_f32 v162, v162, v54, v55
	v_max3_f32 v162, v162, v56, v57
	v_max3_f32 v162, v162, v58, v59
	v_max3_f32 v162, v162, v60, v61
	v_max3_f32 v162, v162, v62, v63
	v_max3_f32 v162, v162, v64, v65
	v_mov_b32_e32 v164, v162
	s_nop 1
	v_permlane32_swap_b32_e32 v162, v164
	v_max_f32_e32 v164, v164, v164
	v_max_f32_e32 v162, v162, v164
	v_add_f32_e32 v164, 0xc1000000, v162
	v_cmp_gt_f32_e32 vcc, v164, v163
	s_cbranch_vccz .LBB0_438
	v_max_f32_e32 v162, v162, v162
	v_max_f32_e32 v164, v163, v163
	v_max_f32_e32 v221, v164, v162
	v_sub_f32_e32 v162, v163, v221
	v_exp_f32_e32 v162, v162
	s_nop 0
	v_mul_f32_e32 v220, v220, v162
	v_pk_mul_f32 v[128:129], v[128:129], v[162:163] op_sel_hi:[1,0]
	v_pk_mul_f32 v[126:127], v[126:127], v[162:163] op_sel_hi:[1,0]
	v_pk_mul_f32 v[124:125], v[124:125], v[162:163] op_sel_hi:[1,0]
	v_pk_mul_f32 v[122:123], v[122:123], v[162:163] op_sel_hi:[1,0]
	v_pk_mul_f32 v[120:121], v[120:121], v[162:163] op_sel_hi:[1,0]
	v_pk_mul_f32 v[118:119], v[118:119], v[162:163] op_sel_hi:[1,0]
	v_pk_mul_f32 v[116:117], v[116:117], v[162:163] op_sel_hi:[1,0]
	v_pk_mul_f32 v[114:115], v[114:115], v[162:163] op_sel_hi:[1,0]
	v_pk_mul_f32 v[112:113], v[112:113], v[162:163] op_sel_hi:[1,0]
	v_pk_mul_f32 v[110:111], v[110:111], v[162:163] op_sel_hi:[1,0]
	v_pk_mul_f32 v[108:109], v[108:109], v[162:163] op_sel_hi:[1,0]
	v_pk_mul_f32 v[106:107], v[106:107], v[162:163] op_sel_hi:[1,0]
	v_pk_mul_f32 v[104:105], v[104:105], v[162:163] op_sel_hi:[1,0]
	v_pk_mul_f32 v[102:103], v[102:103], v[162:163] op_sel_hi:[1,0]
	v_pk_mul_f32 v[100:101], v[100:101], v[162:163] op_sel_hi:[1,0]
	v_pk_mul_f32 v[98:99], v[98:99], v[162:163] op_sel_hi:[1,0]
	s_branch .LBB0_439

.LBB0_439:
	v_sub_f32_e32 v34, v34, v221
	v_exp_f32_e32 v223, v34
	v_sub_f32_e32 v34, v35, v221
	v_exp_f32_e32 v224, v34
	v_sub_f32_e32 v34, v36, v221
	v_exp_f32_e32 v225, v34
	v_sub_f32_e32 v34, v37, v221
	v_exp_f32_e32 v226, v34
	v_sub_f32_e32 v34, v38, v221
	v_exp_f32_e32 v227, v34
	v_sub_f32_e32 v34, v39, v221
	v_exp_f32_e32 v228, v34
	v_sub_f32_e32 v34, v40, v221
	v_exp_f32_e32 v229, v34
	v_sub_f32_e32 v34, v41, v221
	v_exp_f32_e32 v230, v34
	v_sub_f32_e32 v34, v42, v221
	v_exp_f32_e32 v231, v34
	v_sub_f32_e32 v34, v43, v221
	v_exp_f32_e32 v232, v34
	v_sub_f32_e32 v34, v44, v221
	v_exp_f32_e32 v233, v34
	v_sub_f32_e32 v34, v45, v221
	v_exp_f32_e32 v234, v34
	v_sub_f32_e32 v34, v46, v221
	v_exp_f32_e32 v235, v34
	v_sub_f32_e32 v34, v47, v221
	v_exp_f32_e32 v236, v34
	v_sub_f32_e32 v34, v48, v221
	v_exp_f32_e32 v237, v34
	v_sub_f32_e32 v34, v49, v221
	v_exp_f32_e32 v238, v34
	v_sub_f32_e32 v34, v50, v221
	v_exp_f32_e32 v239, v34
	v_sub_f32_e32 v34, v51, v221
	v_exp_f32_e32 v240, v34
	v_sub_f32_e32 v34, v52, v221
	v_exp_f32_e32 v241, v34
	v_sub_f32_e32 v34, v53, v221
	v_exp_f32_e32 v242, v34
	v_sub_f32_e32 v34, v54, v221
	v_exp_f32_e32 v243, v34
	v_sub_f32_e32 v34, v55, v221
	v_exp_f32_e32 v244, v34
	v_sub_f32_e32 v34, v56, v221
	v_lshl_add_u32 v170, s3, 1, v217
	v_exp_f32_e32 v245, v34
	v_sub_f32_e32 v34, v57, v221
	v_exp_f32_e32 v246, v34
	v_sub_f32_e32 v34, v58, v221
	v_add_u32_e32 v38, 0x3000, v170
	v_add_u32_e32 v39, 0x4000, v170
	v_exp_f32_e32 v247, v34
	v_sub_f32_e32 v34, v59, v221
	ds_read2_b64 v[166:169], v38 offset0:128 offset1:130
	ds_read2_b64 v[162:165], v38 offset0:132 offset1:134
	ds_read2_b64 v[170:173], v39 offset0:192 offset1:194
	v_exp_f32_e32 v248, v34
	v_sub_f32_e32 v34, v60, v221
	v_exp_f32_e32 v249, v34
	v_sub_f32_e32 v34, v61, v221
	v_exp_f32_e32 v250, v34
	v_sub_f32_e32 v34, v62, v221
	v_exp_f32_e32 v251, v34
	v_sub_f32_e32 v34, v63, v221
	v_exp_f32_e32 v209, v34
	v_sub_f32_e32 v34, v64, v221
	v_exp_f32_e32 v212, v34
	v_sub_f32_e32 v34, v65, v221
	v_exp_f32_e32 v208, v34
	v_cvt_pk_bf16_f32 v34, v223, v224
	v_cvt_pk_bf16_f32 v35, v225, v226
	v_cvt_pk_bf16_f32 v36, v227, v228
	v_cvt_pk_bf16_f32 v37, v229, v230
	ds_read2_b64 v[174:177], v39 offset0:196 offset1:198
	ds_read2_b64 v[178:181], v38 offset0:136 offset1:138
	s_waitcnt lgkmcnt(4)
	v_mfma_f32_32x32x16_bf16 v[114:129], v[166:169], v[34:37], v[114:129]
	ds_read2_b64 v[182:185], v39 offset0:200 offset1:202
	ds_read2_b64 v[186:189], v38 offset0:140 offset1:142
	v_cvt_pk_bf16_f32 v202, v247, v248
	v_cvt_pk_bf16_f32 v203, v249, v250
	v_cvt_pk_bf16_f32 v204, v251, v209
	v_cvt_pk_bf16_f32 v205, v212, v208
	s_waitcnt lgkmcnt(4)
	v_mfma_f32_32x32x16_bf16 v[98:113], v[170:173], v[34:37], v[98:113]
	v_cvt_pk_bf16_f32 v34, v231, v232
	v_cvt_pk_bf16_f32 v35, v233, v234
	v_cvt_pk_bf16_f32 v36, v235, v236
	v_cvt_pk_bf16_f32 v37, v237, v238
	s_nop 1
	v_mfma_f32_32x32x16_bf16 v[114:129], v[162:165], v[34:37], v[114:129]
	s_waitcnt lgkmcnt(3)
	v_mfma_f32_32x32x16_bf16 v[98:113], v[174:177], v[34:37], v[98:113]
	v_cvt_pk_bf16_f32 v34, v239, v240
	v_cvt_pk_bf16_f32 v35, v241, v242
	v_cvt_pk_bf16_f32 v36, v243, v244
	v_cvt_pk_bf16_f32 v37, v245, v246
	s_waitcnt lgkmcnt(2)
	s_nop 0
	v_mfma_f32_32x32x16_bf16 v[114:129], v[178:181], v[34:37], v[114:129]
	s_waitcnt lgkmcnt(1)
	v_mfma_f32_32x32x16_bf16 v[98:113], v[182:185], v[34:37], v[98:113]
	ds_read2_b64 v[44:47], v39 offset0:204 offset1:206
	v_max_f32_e32 v34, v19, v19
	v_max_f32_e32 v35, v18, v18
	v_max_f32_e32 v34, v35, v34
	v_max3_f32 v34, v34, v20, v21
	v_max3_f32 v34, v34, v22, v23
	v_max3_f32 v34, v34, v24, v25
	v_max3_f32 v34, v34, v26, v27
	v_max3_f32 v34, v34, v28, v29
	v_max3_f32 v34, v34, v30, v31
	v_max3_f32 v34, v34, v32, v33
	v_max3_f32 v34, v34, v2, v3
	v_max3_f32 v34, v34, v4, v5
	v_max3_f32 v34, v34, v6, v7
	v_max3_f32 v34, v34, v8, v9
	v_max3_f32 v34, v34, v10, v11
	v_max3_f32 v34, v34, v12, v13
	v_max3_f32 v34, v34, v14, v15
	v_max3_f32 v34, v34, v16, v17
	s_waitcnt lgkmcnt(1)
	v_mfma_f32_32x32x16_bf16 v[114:129], v[186:189], v[202:205], v[114:129]
	v_mov_b32_e32 v35, v34
	s_nop 1
	v_permlane32_swap_b32_e32 v34, v35
	s_waitcnt lgkmcnt(0)
	v_max_f32_e32 v35, v35, v35
	v_max_f32_e32 v34, v34, v35
	v_mfma_f32_32x32x16_bf16 v[98:113], v[44:47], v[202:205], v[98:113]
	v_add_f32_e32 v35, 0xc1000000, v34
	v_cmp_gt_f32_e32 vcc, v35, v0
	s_cbranch_vccz .LBB0_441
	v_max_f32_e32 v34, v34, v34
	v_max_f32_e32 v35, v0, v0
	v_max_f32_e32 v34, v35, v34
	v_sub_f32_e32 v0, v0, v34
	v_exp_f32_e32 v0, v0
	s_nop 0
	v_mul_f32_e32 v219, v219, v0
	v_pk_mul_f32 v[96:97], v[96:97], v[0:1] op_sel_hi:[1,0]
	v_pk_mul_f32 v[94:95], v[94:95], v[0:1] op_sel_hi:[1,0]
	v_pk_mul_f32 v[92:93], v[92:93], v[0:1] op_sel_hi:[1,0]
	v_pk_mul_f32 v[90:91], v[90:91], v[0:1] op_sel_hi:[1,0]
	v_pk_mul_f32 v[88:89], v[88:89], v[0:1] op_sel_hi:[1,0]
	v_pk_mul_f32 v[86:87], v[86:87], v[0:1] op_sel_hi:[1,0]
	v_pk_mul_f32 v[84:85], v[84:85], v[0:1] op_sel_hi:[1,0]
	v_pk_mul_f32 v[82:83], v[82:83], v[0:1] op_sel_hi:[1,0]
	v_pk_mul_f32 v[80:81], v[80:81], v[0:1] op_sel_hi:[1,0]
	v_pk_mul_f32 v[78:79], v[78:79], v[0:1] op_sel_hi:[1,0]
	v_pk_mul_f32 v[76:77], v[76:77], v[0:1] op_sel_hi:[1,0]
	v_pk_mul_f32 v[74:75], v[74:75], v[0:1] op_sel_hi:[1,0]
	v_pk_mul_f32 v[72:73], v[72:73], v[0:1] op_sel_hi:[1,0]
	v_pk_mul_f32 v[70:71], v[70:71], v[0:1] op_sel_hi:[1,0]
	v_pk_mul_f32 v[68:69], v[68:69], v[0:1] op_sel_hi:[1,0]
	v_pk_mul_f32 v[66:67], v[66:67], v[0:1] op_sel_hi:[1,0]
	v_mov_b32_e32 v0, v34
